# GEMM K-loops: zig-zag MFMA order - consecutive MFMAs share the accumulator (forwarded SrcC) or one A/B operand; k order alternates per accumulator (f32 accumulation order only)
# speedup vs baseline: 1.0133x; 1.0055x over previous
.LBB0_127:
	s_add_u32 s2, s0, 0xfff80080
	s_addc_u32 s3, s1, -1
	s_add_i32 s50, 0, 0x10000
	s_cmp_eq_u32 s49, 28
	s_cselect_b32 s5, s23, s3
	s_cselect_b32 s4, s27, s2
	s_cselect_b32 s3, s9, s48
	s_cselect_b32 s2, s46, s47
	s_add_i32 s52, 0, 0x14000
	v_add_u32_e32 v154, s50, v163
	v_add_u32_e32 v176, s52, v163
	ds_read_b128 v[142:145], v154
	ds_read_b128 v[146:149], v154 offset:1024
	ds_read_b128 v[150:153], v154 offset:2048
	ds_read_b128 v[154:157], v154 offset:3072
	ds_read_b128 v[158:161], v176
	ds_read_b128 v[168:171], v176 offset:1024
	ds_read_b128 v[172:175], v176 offset:2048
	ds_read_b128 v[176:179], v176 offset:3072
	v_lshl_add_u64 v[204:205], s[0:1], 0, v[138:139]
	s_add_i32 m0, s11, 0xc000
	ds_read_b128 v[180:183], v167
	ds_read_b128 v[184:187], v167 offset:1024
	ds_read_b128 v[188:191], v167 offset:2048
	ds_read_b128 v[192:195], v167 offset:3072
	ds_read_b128 v[196:199], v167 offset:4096
	ds_read_b128 v[200:203], v167 offset:5120
	ds_read_b128 v[210:213], v167 offset:6144
	ds_read_b128 v[214:217], v167 offset:7168
	global_load_lds_dwordx4 v[204:205], off
	v_lshl_add_u64 v[204:205], s[0:1], 0, v[140:141]
	s_add_i32 m0, s11, 0xe000
	s_nop 0
	global_load_lds_dwordx4 v[204:205], off
	s_waitcnt vmcnt(8)
	s_waitcnt lgkmcnt(0)
	s_barrier
	s_setprio 1
	s_waitcnt lgkmcnt(0)
	v_mfma_f32_16x16x32_bf16 v[126:129], v[142:145], v[180:183], v[126:129]
	v_mfma_f32_16x16x32_bf16 v[126:129], v[146:149], v[184:187], v[126:129]
	v_mfma_f32_16x16x32_bf16 v[122:125], v[154:157], v[184:187], v[122:125]
	v_mfma_f32_16x16x32_bf16 v[122:125], v[150:153], v[180:183], v[122:125]
	v_mfma_f32_16x16x32_bf16 v[106:109], v[150:153], v[188:191], v[106:109]
	v_mfma_f32_16x16x32_bf16 v[106:109], v[154:157], v[192:195], v[106:109]
	v_mfma_f32_16x16x32_bf16 v[110:113], v[146:149], v[192:195], v[110:113]
	v_mfma_f32_16x16x32_bf16 v[110:113], v[142:145], v[188:191], v[110:113]
	v_mfma_f32_16x16x32_bf16 v[94:97], v[142:145], v[196:199], v[94:97]
	v_mfma_f32_16x16x32_bf16 v[94:97], v[146:149], v[200:203], v[94:97]
	v_mfma_f32_16x16x32_bf16 v[90:93], v[154:157], v[200:203], v[90:93]
	v_mfma_f32_16x16x32_bf16 v[90:93], v[150:153], v[196:199], v[90:93]
	v_mfma_f32_16x16x32_bf16 v[74:77], v[150:153], v[210:213], v[74:77]
	v_mfma_f32_16x16x32_bf16 v[74:77], v[154:157], v[214:217], v[74:77]
	v_mfma_f32_16x16x32_bf16 v[78:81], v[146:149], v[214:217], v[78:81]
	v_mfma_f32_16x16x32_bf16 v[78:81], v[142:145], v[210:213], v[78:81]
	s_setprio 0
	s_setprio 1
	v_mfma_f32_16x16x32_bf16 v[118:121], v[158:161], v[180:183], v[118:121]
	v_mfma_f32_16x16x32_bf16 v[118:121], v[168:171], v[184:187], v[118:121]
	v_mfma_f32_16x16x32_bf16 v[114:117], v[176:179], v[184:187], v[114:117]
	v_mfma_f32_16x16x32_bf16 v[114:117], v[172:175], v[180:183], v[114:117]
	v_mfma_f32_16x16x32_bf16 v[98:101], v[172:175], v[188:191], v[98:101]
	v_mfma_f32_16x16x32_bf16 v[98:101], v[176:179], v[192:195], v[98:101]
	v_mfma_f32_16x16x32_bf16 v[102:105], v[168:171], v[192:195], v[102:105]
	v_mfma_f32_16x16x32_bf16 v[102:105], v[158:161], v[188:191], v[102:105]
	v_mfma_f32_16x16x32_bf16 v[86:89], v[158:161], v[196:199], v[86:89]
	v_mfma_f32_16x16x32_bf16 v[86:89], v[168:171], v[200:203], v[86:89]
	v_mfma_f32_16x16x32_bf16 v[82:85], v[176:179], v[200:203], v[82:85]
	v_mfma_f32_16x16x32_bf16 v[82:85], v[172:175], v[196:199], v[82:85]
	v_mfma_f32_16x16x32_bf16 v[66:69], v[172:175], v[210:213], v[66:69]
	v_mfma_f32_16x16x32_bf16 v[66:69], v[176:179], v[214:217], v[66:69]
	v_mfma_f32_16x16x32_bf16 v[70:73], v[168:171], v[214:217], v[70:73]
	v_mfma_f32_16x16x32_bf16 v[70:73], v[158:161], v[210:213], v[70:73]
	s_setprio 0
	s_barrier
	s_add_i32 s50, s50, s31
	v_lshl_add_u64 v[204:205], s[2:3], 0, v[0:1]
	s_mov_b32 m0, s50
	ds_read_b128 v[180:183], v167 offset:16384
	ds_read_b128 v[184:187], v167 offset:17408
	ds_read_b128 v[188:191], v167 offset:18432
	ds_read_b128 v[192:195], v167 offset:19456
	ds_read_b128 v[196:199], v167 offset:20480
	ds_read_b128 v[200:203], v167 offset:21504
	ds_read_b128 v[210:213], v167 offset:22528
	ds_read_b128 v[214:217], v167 offset:23552
	global_load_lds_dwordx4 v[204:205], off
	s_add_i32 m0, s50, 0x2000
	s_add_u32 s50, s2, 0x80000
	v_lshl_add_u64 v[206:207], s[2:3], 0, v[134:135]
	s_addc_u32 s51, s3, 0
	s_add_i32 s52, s52, s31
	global_load_lds_dwordx4 v[206:207], off
	v_lshl_add_u64 v[218:219], s[50:51], 0, v[0:1]
	s_mov_b32 m0, s52
	v_lshl_add_u64 v[220:221], s[4:5], 0, v[132:133]
	global_load_lds_dwordx4 v[218:219], off
	v_lshl_add_u64 v[218:219], s[50:51], 0, v[134:135]
	s_add_i32 m0, s52, 0x2000
	s_nop 0
	global_load_lds_dwordx4 v[218:219], off
	v_lshl_add_u64 v[218:219], s[4:5], 0, v[130:131]
	s_mov_b32 m0, s11
	s_nop 0
	global_load_lds_dwordx4 v[218:219], off
	s_mov_b32 m0, s35
	s_nop 0
	global_load_lds_dwordx4 v[220:221], off
	s_waitcnt vmcnt(8)
	s_waitcnt lgkmcnt(0)
	s_barrier
	s_setprio 1
	s_waitcnt lgkmcnt(0)
	v_mfma_f32_16x16x32_bf16 v[62:65], v[142:145], v[180:183], v[62:65]
	v_mfma_f32_16x16x32_bf16 v[62:65], v[146:149], v[184:187], v[62:65]
	v_mfma_f32_16x16x32_bf16 v[58:61], v[154:157], v[184:187], v[58:61]
	v_mfma_f32_16x16x32_bf16 v[58:61], v[150:153], v[180:183], v[58:61]
	v_mfma_f32_16x16x32_bf16 v[42:45], v[150:153], v[188:191], v[42:45]
	v_mfma_f32_16x16x32_bf16 v[42:45], v[154:157], v[192:195], v[42:45]
	v_mfma_f32_16x16x32_bf16 v[46:49], v[146:149], v[192:195], v[46:49]
	v_mfma_f32_16x16x32_bf16 v[46:49], v[142:145], v[188:191], v[46:49]
	v_mfma_f32_16x16x32_bf16 v[30:33], v[142:145], v[196:199], v[30:33]
	v_mfma_f32_16x16x32_bf16 v[30:33], v[146:149], v[200:203], v[30:33]
	v_mfma_f32_16x16x32_bf16 v[26:29], v[154:157], v[200:203], v[26:29]
	v_mfma_f32_16x16x32_bf16 v[26:29], v[150:153], v[196:199], v[26:29]
	v_mfma_f32_16x16x32_bf16 v[10:13], v[150:153], v[210:213], v[10:13]
	v_mfma_f32_16x16x32_bf16 v[10:13], v[154:157], v[214:217], v[10:13]
	v_mfma_f32_16x16x32_bf16 v[14:17], v[146:149], v[214:217], v[14:17]
	v_mfma_f32_16x16x32_bf16 v[14:17], v[142:145], v[210:213], v[14:17]
	s_setprio 0
	s_setprio 1
	v_mfma_f32_16x16x32_bf16 v[54:57], v[158:161], v[180:183], v[54:57]
	v_mfma_f32_16x16x32_bf16 v[54:57], v[168:171], v[184:187], v[54:57]
	v_mfma_f32_16x16x32_bf16 v[50:53], v[176:179], v[184:187], v[50:53]
	v_mfma_f32_16x16x32_bf16 v[50:53], v[172:175], v[180:183], v[50:53]
	v_mfma_f32_16x16x32_bf16 v[34:37], v[172:175], v[188:191], v[34:37]
	v_mfma_f32_16x16x32_bf16 v[34:37], v[176:179], v[192:195], v[34:37]
	v_mfma_f32_16x16x32_bf16 v[38:41], v[168:171], v[192:195], v[38:41]
	v_mfma_f32_16x16x32_bf16 v[38:41], v[158:161], v[188:191], v[38:41]
	v_mfma_f32_16x16x32_bf16 v[22:25], v[158:161], v[196:199], v[22:25]
	v_mfma_f32_16x16x32_bf16 v[22:25], v[168:171], v[200:203], v[22:25]
	v_mfma_f32_16x16x32_bf16 v[18:21], v[176:179], v[200:203], v[18:21]
	v_mfma_f32_16x16x32_bf16 v[18:21], v[172:175], v[196:199], v[18:21]
	v_mfma_f32_16x16x32_bf16 v[2:5], v[172:175], v[210:213], v[2:5]
	v_mfma_f32_16x16x32_bf16 v[2:5], v[176:179], v[214:217], v[2:5]
	v_mfma_f32_16x16x32_bf16 v[6:9], v[168:171], v[214:217], v[6:9]
	v_mfma_f32_16x16x32_bf16 v[6:9], v[158:161], v[210:213], v[6:9]
	s_setprio 0
	s_barrier
	s_add_i32 s50, 0, 0x18000
	s_add_i32 s51, 0, 0x1c000
	v_add_u32_e32 v154, s50, v163
	v_add_u32_e32 v176, s51, v163
	ds_read_b128 v[142:145], v154
	ds_read_b128 v[146:149], v154 offset:1024
	ds_read_b128 v[150:153], v154 offset:2048
	ds_read_b128 v[154:157], v154 offset:3072
	ds_read_b128 v[158:161], v176
	ds_read_b128 v[168:171], v176 offset:1024
	ds_read_b128 v[172:175], v176 offset:2048
	ds_read_b128 v[176:179], v176 offset:3072
	s_add_u32 s4, s4, 0x80000
	s_addc_u32 s5, s5, 0
	s_mov_b32 m0, s36
	v_lshl_add_u64 v[222:223], s[4:5], 0, v[130:131]
	ds_read_b128 v[180:183], v167 offset:32768
	ds_read_b128 v[184:187], v167 offset:33792
	ds_read_b128 v[188:191], v167 offset:34816
	ds_read_b128 v[192:195], v167 offset:35840
	ds_read_b128 v[196:199], v167 offset:36864
	ds_read_b128 v[200:203], v167 offset:37888
	ds_read_b128 v[210:213], v167 offset:38912
	ds_read_b128 v[214:217], v167 offset:39936
	global_load_lds_dwordx4 v[222:223], off
	v_lshl_add_u64 v[222:223], s[4:5], 0, v[132:133]
	s_mov_b32 m0, s37
	s_nop 0
	global_load_lds_dwordx4 v[222:223], off
	s_waitcnt vmcnt(8)
	s_waitcnt lgkmcnt(0)
	s_barrier
	s_setprio 1
	s_waitcnt lgkmcnt(0)
	v_mfma_f32_16x16x32_bf16 v[126:129], v[142:145], v[180:183], v[126:129]
	v_mfma_f32_16x16x32_bf16 v[126:129], v[146:149], v[184:187], v[126:129]
	v_mfma_f32_16x16x32_bf16 v[122:125], v[154:157], v[184:187], v[122:125]
	v_mfma_f32_16x16x32_bf16 v[122:125], v[150:153], v[180:183], v[122:125]
	v_mfma_f32_16x16x32_bf16 v[106:109], v[150:153], v[188:191], v[106:109]
	v_mfma_f32_16x16x32_bf16 v[106:109], v[154:157], v[192:195], v[106:109]
	v_mfma_f32_16x16x32_bf16 v[110:113], v[146:149], v[192:195], v[110:113]
	v_mfma_f32_16x16x32_bf16 v[110:113], v[142:145], v[188:191], v[110:113]
	v_mfma_f32_16x16x32_bf16 v[94:97], v[142:145], v[196:199], v[94:97]
	v_mfma_f32_16x16x32_bf16 v[94:97], v[146:149], v[200:203], v[94:97]
	v_mfma_f32_16x16x32_bf16 v[90:93], v[154:157], v[200:203], v[90:93]
	v_mfma_f32_16x16x32_bf16 v[90:93], v[150:153], v[196:199], v[90:93]
	v_mfma_f32_16x16x32_bf16 v[74:77], v[150:153], v[210:213], v[74:77]
	v_mfma_f32_16x16x32_bf16 v[74:77], v[154:157], v[214:217], v[74:77]
	v_mfma_f32_16x16x32_bf16 v[78:81], v[146:149], v[214:217], v[78:81]
	v_mfma_f32_16x16x32_bf16 v[78:81], v[142:145], v[210:213], v[78:81]
	s_setprio 0
	s_setprio 1
	v_mfma_f32_16x16x32_bf16 v[118:121], v[158:161], v[180:183], v[118:121]
	v_mfma_f32_16x16x32_bf16 v[118:121], v[168:171], v[184:187], v[118:121]
	v_mfma_f32_16x16x32_bf16 v[114:117], v[176:179], v[184:187], v[114:117]
	v_mfma_f32_16x16x32_bf16 v[114:117], v[172:175], v[180:183], v[114:117]
	v_mfma_f32_16x16x32_bf16 v[98:101], v[172:175], v[188:191], v[98:101]
	v_mfma_f32_16x16x32_bf16 v[98:101], v[176:179], v[192:195], v[98:101]
	v_mfma_f32_16x16x32_bf16 v[102:105], v[168:171], v[192:195], v[102:105]
	v_mfma_f32_16x16x32_bf16 v[102:105], v[158:161], v[188:191], v[102:105]
	v_mfma_f32_16x16x32_bf16 v[86:89], v[158:161], v[196:199], v[86:89]
	v_mfma_f32_16x16x32_bf16 v[86:89], v[168:171], v[200:203], v[86:89]
	v_mfma_f32_16x16x32_bf16 v[82:85], v[176:179], v[200:203], v[82:85]
	v_mfma_f32_16x16x32_bf16 v[82:85], v[172:175], v[196:199], v[82:85]
	v_mfma_f32_16x16x32_bf16 v[66:69], v[172:175], v[210:213], v[66:69]
	v_mfma_f32_16x16x32_bf16 v[66:69], v[176:179], v[214:217], v[66:69]
	v_mfma_f32_16x16x32_bf16 v[70:73], v[168:171], v[214:217], v[70:73]
	v_mfma_f32_16x16x32_bf16 v[70:73], v[158:161], v[210:213], v[70:73]
	s_setprio 0
	s_barrier
	s_add_i32 s4, s50, s31
	v_lshl_add_u64 v[204:205], v[204:205], 0, s[68:69]
	s_mov_b32 m0, s4
	ds_read_b128 v[180:183], v167 offset:49152
	ds_read_b128 v[184:187], v167 offset:50176
	ds_read_b128 v[188:191], v167 offset:51200
	ds_read_b128 v[192:195], v167 offset:52224
	ds_read_b128 v[196:199], v167 offset:53248
	ds_read_b128 v[200:203], v167 offset:54272
	ds_read_b128 v[210:213], v167 offset:55296
	ds_read_b128 v[214:217], v167 offset:56320
	global_load_lds_dwordx4 v[204:205], off
	s_add_i32 m0, s4, 0x2000
	s_add_u32 s2, s2, 0x80080
	v_lshl_add_u64 v[204:205], v[206:207], 0, s[68:69]
	s_addc_u32 s3, s3, 0
	s_add_i32 s4, s51, s31
	global_load_lds_dwordx4 v[204:205], off
	v_lshl_add_u64 v[204:205], s[2:3], 0, v[0:1]
	s_mov_b32 m0, s4
	s_nop 0
	global_load_lds_dwordx4 v[204:205], off
	v_lshl_add_u64 v[204:205], s[2:3], 0, v[134:135]
	s_add_i32 m0, s4, 0x2000
	s_nop 0
	global_load_lds_dwordx4 v[204:205], off
	v_lshl_add_u64 v[204:205], v[218:219], 0, s[68:69]
	s_mov_b32 m0, s38
	s_nop 0
	global_load_lds_dwordx4 v[204:205], off
	v_lshl_add_u64 v[204:205], v[220:221], 0, s[68:69]
	s_mov_b32 m0, s39
	s_nop 0
	global_load_lds_dwordx4 v[204:205], off
	s_waitcnt vmcnt(8)
	s_waitcnt lgkmcnt(0)
	s_barrier
	s_setprio 1
	s_waitcnt lgkmcnt(0)
	v_mfma_f32_16x16x32_bf16 v[62:65], v[142:145], v[180:183], v[62:65]
	v_mfma_f32_16x16x32_bf16 v[62:65], v[146:149], v[184:187], v[62:65]
	v_mfma_f32_16x16x32_bf16 v[58:61], v[154:157], v[184:187], v[58:61]
	v_mfma_f32_16x16x32_bf16 v[58:61], v[150:153], v[180:183], v[58:61]
	v_mfma_f32_16x16x32_bf16 v[42:45], v[150:153], v[188:191], v[42:45]
	v_mfma_f32_16x16x32_bf16 v[42:45], v[154:157], v[192:195], v[42:45]
	v_mfma_f32_16x16x32_bf16 v[46:49], v[146:149], v[192:195], v[46:49]
	v_mfma_f32_16x16x32_bf16 v[46:49], v[142:145], v[188:191], v[46:49]
	v_mfma_f32_16x16x32_bf16 v[30:33], v[142:145], v[196:199], v[30:33]
	v_mfma_f32_16x16x32_bf16 v[30:33], v[146:149], v[200:203], v[30:33]
	v_mfma_f32_16x16x32_bf16 v[26:29], v[154:157], v[200:203], v[26:29]
	v_mfma_f32_16x16x32_bf16 v[26:29], v[150:153], v[196:199], v[26:29]
	v_mfma_f32_16x16x32_bf16 v[10:13], v[150:153], v[210:213], v[10:13]
	v_mfma_f32_16x16x32_bf16 v[10:13], v[154:157], v[214:217], v[10:13]
	v_mfma_f32_16x16x32_bf16 v[14:17], v[146:149], v[214:217], v[14:17]
	v_mfma_f32_16x16x32_bf16 v[14:17], v[142:145], v[210:213], v[14:17]
	s_setprio 0
	s_setprio 1
	v_mfma_f32_16x16x32_bf16 v[54:57], v[158:161], v[180:183], v[54:57]
	v_mfma_f32_16x16x32_bf16 v[54:57], v[168:171], v[184:187], v[54:57]
	v_mfma_f32_16x16x32_bf16 v[50:53], v[176:179], v[184:187], v[50:53]
	v_mfma_f32_16x16x32_bf16 v[50:53], v[172:175], v[180:183], v[50:53]
	v_mfma_f32_16x16x32_bf16 v[34:37], v[172:175], v[188:191], v[34:37]
	v_mfma_f32_16x16x32_bf16 v[34:37], v[176:179], v[192:195], v[34:37]
	v_mfma_f32_16x16x32_bf16 v[38:41], v[168:171], v[192:195], v[38:41]
	v_mfma_f32_16x16x32_bf16 v[38:41], v[158:161], v[188:191], v[38:41]
	v_mfma_f32_16x16x32_bf16 v[22:25], v[158:161], v[196:199], v[22:25]
	v_mfma_f32_16x16x32_bf16 v[22:25], v[168:171], v[200:203], v[22:25]
	v_mfma_f32_16x16x32_bf16 v[18:21], v[176:179], v[200:203], v[18:21]
	v_mfma_f32_16x16x32_bf16 v[18:21], v[172:175], v[196:199], v[18:21]
	v_mfma_f32_16x16x32_bf16 v[2:5], v[172:175], v[210:213], v[2:5]
	v_mfma_f32_16x16x32_bf16 v[2:5], v[176:179], v[214:217], v[2:5]
	v_mfma_f32_16x16x32_bf16 v[6:9], v[168:171], v[214:217], v[6:9]
	v_mfma_f32_16x16x32_bf16 v[6:9], v[158:161], v[210:213], v[6:9]
	s_setprio 0
	s_barrier
	s_add_i32 s49, s49, 2
	s_add_u32 s0, s0, 0x100
	s_addc_u32 s1, s1, 0
	s_add_u32 s47, s47, 0x100
	s_addc_u32 s48, s48, 0
	s_cmp_gt_u32 s49, 29
	s_cbranch_scc0 .LBB0_127
	s_and_b64 vcc, exec, s[18:19]
	s_cbranch_vccz .LBB0_130
	s_barrier

.LBB0_376:
	s_add_u32 s10, s22, s8
	s_addc_u32 s11, s23, s9
	s_add_u32 s10, s10, 0x14100100
	s_addc_u32 s11, s11, 0
	s_add_u32 s27, s24, s8
	s_addc_u32 s28, s25, s9
	s_cmpk_eq_i32 s8, 0xf00
	s_cselect_b32 s13, s7, s11
	s_cselect_b32 s12, s6, s10
	s_cselect_b32 s11, s3, s28
	s_cselect_b32 s10, s2, s27
	s_add_i32 s27, 0, 0x14000
	v_add_u32_e32 v143, s27, v141
	s_add_i32 s28, 0, 0x10000
	ds_read_b128 v[144:147], v143 offset:3072
	ds_read_b128 v[148:151], v143 offset:2048
	ds_read_b128 v[152:155], v143 offset:1024
	ds_read_b128 v[156:159], v143
	v_add_u32_e32 v143, s28, v141
	ds_read_b128 v[160:163], v143 offset:3072
	ds_read_b128 v[164:167], v143 offset:2048
	ds_read_b128 v[168:171], v143 offset:1024
	ds_read_b128 v[174:177], v143
	v_lshl_add_u64 v[206:207], v[136:137], 0, s[8:9]
	s_add_i32 m0, s19, 0xc000
	ds_read_b128 v[178:181], v142
	ds_read_b128 v[182:185], v142 offset:1024
	ds_read_b128 v[186:189], v142 offset:2048
	ds_read_b128 v[190:193], v142 offset:3072
	ds_read_b128 v[194:197], v142 offset:4096
	ds_read_b128 v[198:201], v142 offset:5120
	ds_read_b128 v[202:205], v142 offset:6144
	ds_read_b128 v[210:213], v142 offset:7168
	global_load_lds_dwordx4 v[206:207], off
	v_lshl_add_u64 v[206:207], v[138:139], 0, s[8:9]
	s_add_i32 m0, s19, 0xe000
	s_nop 0
	global_load_lds_dwordx4 v[206:207], off
	s_waitcnt vmcnt(8)
	s_waitcnt lgkmcnt(0)
	s_barrier
	s_setprio 1
	s_waitcnt lgkmcnt(0)
	v_mfma_f32_16x16x32_bf16 v[126:129], v[174:177], v[178:181], v[126:129]
	v_mfma_f32_16x16x32_bf16 v[126:129], v[168:171], v[182:185], v[126:129]
	v_mfma_f32_16x16x32_bf16 v[122:125], v[160:163], v[182:185], v[122:125]
	v_mfma_f32_16x16x32_bf16 v[122:125], v[164:167], v[178:181], v[122:125]
	v_mfma_f32_16x16x32_bf16 v[106:109], v[164:167], v[186:189], v[106:109]
	v_mfma_f32_16x16x32_bf16 v[106:109], v[160:163], v[190:193], v[106:109]
	v_mfma_f32_16x16x32_bf16 v[110:113], v[168:171], v[190:193], v[110:113]
	v_mfma_f32_16x16x32_bf16 v[110:113], v[174:177], v[186:189], v[110:113]
	v_mfma_f32_16x16x32_bf16 v[94:97], v[174:177], v[194:197], v[94:97]
	v_mfma_f32_16x16x32_bf16 v[94:97], v[168:171], v[198:201], v[94:97]
	v_mfma_f32_16x16x32_bf16 v[90:93], v[160:163], v[198:201], v[90:93]
	v_mfma_f32_16x16x32_bf16 v[90:93], v[164:167], v[194:197], v[90:93]
	v_mfma_f32_16x16x32_bf16 v[74:77], v[164:167], v[202:205], v[74:77]
	v_mfma_f32_16x16x32_bf16 v[74:77], v[160:163], v[210:213], v[74:77]
	v_mfma_f32_16x16x32_bf16 v[78:81], v[168:171], v[210:213], v[78:81]
	v_mfma_f32_16x16x32_bf16 v[78:81], v[174:177], v[202:205], v[78:81]
	s_setprio 0
	s_setprio 1
	v_mfma_f32_16x16x32_bf16 v[118:121], v[156:159], v[178:181], v[118:121]
	v_mfma_f32_16x16x32_bf16 v[118:121], v[152:155], v[182:185], v[118:121]
	v_mfma_f32_16x16x32_bf16 v[114:117], v[144:147], v[182:185], v[114:117]
	v_mfma_f32_16x16x32_bf16 v[114:117], v[148:151], v[178:181], v[114:117]
	v_mfma_f32_16x16x32_bf16 v[98:101], v[148:151], v[186:189], v[98:101]
	v_mfma_f32_16x16x32_bf16 v[98:101], v[144:147], v[190:193], v[98:101]
	v_mfma_f32_16x16x32_bf16 v[102:105], v[152:155], v[190:193], v[102:105]
	v_mfma_f32_16x16x32_bf16 v[102:105], v[156:159], v[186:189], v[102:105]
	v_mfma_f32_16x16x32_bf16 v[86:89], v[156:159], v[194:197], v[86:89]
	v_mfma_f32_16x16x32_bf16 v[86:89], v[152:155], v[198:201], v[86:89]
	v_mfma_f32_16x16x32_bf16 v[82:85], v[144:147], v[198:201], v[82:85]
	v_mfma_f32_16x16x32_bf16 v[82:85], v[148:151], v[194:197], v[82:85]
	v_mfma_f32_16x16x32_bf16 v[66:69], v[148:151], v[202:205], v[66:69]
	v_mfma_f32_16x16x32_bf16 v[66:69], v[144:147], v[210:213], v[66:69]
	v_mfma_f32_16x16x32_bf16 v[70:73], v[152:155], v[210:213], v[70:73]
	v_mfma_f32_16x16x32_bf16 v[70:73], v[156:159], v[202:205], v[70:73]
	s_setprio 0
	s_barrier
	s_add_i32 s28, s28, s18
	v_lshl_add_u64 v[206:207], s[10:11], 0, v[0:1]
	s_mov_b32 m0, s28
	ds_read_b128 v[178:181], v142 offset:16384
	ds_read_b128 v[182:185], v142 offset:17408
	ds_read_b128 v[186:189], v142 offset:18432
	ds_read_b128 v[190:193], v142 offset:19456
	ds_read_b128 v[194:197], v142 offset:20480
	ds_read_b128 v[198:201], v142 offset:21504
	ds_read_b128 v[202:205], v142 offset:22528
	ds_read_b128 v[210:213], v142 offset:23552
	global_load_lds_dwordx4 v[206:207], off
	s_add_i32 m0, s28, 0x2000
	s_add_u32 s28, s10, 0x80000
	v_lshl_add_u64 v[214:215], s[10:11], 0, v[130:131]
	s_addc_u32 s29, s11, 0
	s_add_i32 s27, s27, s18
	global_load_lds_dwordx4 v[214:215], off
	v_lshl_add_u64 v[216:217], s[28:29], 0, v[0:1]
	s_mov_b32 m0, s27
	v_lshl_add_u64 v[218:219], s[12:13], 0, v[134:135]
	global_load_lds_dwordx4 v[216:217], off
	v_lshl_add_u64 v[216:217], s[28:29], 0, v[130:131]
	s_add_i32 m0, s27, 0x2000
	s_nop 0
	global_load_lds_dwordx4 v[216:217], off
	v_lshl_add_u64 v[216:217], s[12:13], 0, v[132:133]
	s_mov_b32 m0, s19
	s_nop 0
	global_load_lds_dwordx4 v[216:217], off
	s_mov_b32 m0, s1
	s_nop 0
	global_load_lds_dwordx4 v[218:219], off
	s_waitcnt vmcnt(8)
	s_waitcnt lgkmcnt(0)
	s_barrier
	s_setprio 1
	s_waitcnt lgkmcnt(0)
	v_mfma_f32_16x16x32_bf16 v[62:65], v[174:177], v[178:181], v[62:65]
	v_mfma_f32_16x16x32_bf16 v[62:65], v[168:171], v[182:185], v[62:65]
	v_mfma_f32_16x16x32_bf16 v[58:61], v[160:163], v[182:185], v[58:61]
	v_mfma_f32_16x16x32_bf16 v[58:61], v[164:167], v[178:181], v[58:61]
	v_mfma_f32_16x16x32_bf16 v[42:45], v[164:167], v[186:189], v[42:45]
	v_mfma_f32_16x16x32_bf16 v[42:45], v[160:163], v[190:193], v[42:45]
	v_mfma_f32_16x16x32_bf16 v[46:49], v[168:171], v[190:193], v[46:49]
	v_mfma_f32_16x16x32_bf16 v[46:49], v[174:177], v[186:189], v[46:49]
	v_mfma_f32_16x16x32_bf16 v[30:33], v[174:177], v[194:197], v[30:33]
	v_mfma_f32_16x16x32_bf16 v[30:33], v[168:171], v[198:201], v[30:33]
	v_mfma_f32_16x16x32_bf16 v[26:29], v[160:163], v[198:201], v[26:29]
	v_mfma_f32_16x16x32_bf16 v[26:29], v[164:167], v[194:197], v[26:29]
	v_mfma_f32_16x16x32_bf16 v[10:13], v[164:167], v[202:205], v[10:13]
	v_mfma_f32_16x16x32_bf16 v[10:13], v[160:163], v[210:213], v[10:13]
	v_mfma_f32_16x16x32_bf16 v[14:17], v[168:171], v[210:213], v[14:17]
	v_mfma_f32_16x16x32_bf16 v[14:17], v[174:177], v[202:205], v[14:17]
	s_setprio 0
	s_setprio 1
	v_mfma_f32_16x16x32_bf16 v[54:57], v[156:159], v[178:181], v[54:57]
	v_mfma_f32_16x16x32_bf16 v[54:57], v[152:155], v[182:185], v[54:57]
	v_mfma_f32_16x16x32_bf16 v[50:53], v[144:147], v[182:185], v[50:53]
	v_mfma_f32_16x16x32_bf16 v[50:53], v[148:151], v[178:181], v[50:53]
	v_mfma_f32_16x16x32_bf16 v[34:37], v[148:151], v[186:189], v[34:37]
	v_mfma_f32_16x16x32_bf16 v[34:37], v[144:147], v[190:193], v[34:37]
	v_mfma_f32_16x16x32_bf16 v[38:41], v[152:155], v[190:193], v[38:41]
	v_mfma_f32_16x16x32_bf16 v[38:41], v[156:159], v[186:189], v[38:41]
	v_mfma_f32_16x16x32_bf16 v[22:25], v[156:159], v[194:197], v[22:25]
	v_mfma_f32_16x16x32_bf16 v[22:25], v[152:155], v[198:201], v[22:25]
	v_mfma_f32_16x16x32_bf16 v[18:21], v[144:147], v[198:201], v[18:21]
	v_mfma_f32_16x16x32_bf16 v[18:21], v[148:151], v[194:197], v[18:21]
	v_mfma_f32_16x16x32_bf16 v[2:5], v[148:151], v[202:205], v[2:5]
	v_mfma_f32_16x16x32_bf16 v[2:5], v[144:147], v[210:213], v[2:5]
	v_mfma_f32_16x16x32_bf16 v[6:9], v[152:155], v[210:213], v[6:9]
	v_mfma_f32_16x16x32_bf16 v[6:9], v[156:159], v[202:205], v[6:9]
	s_setprio 0
	s_barrier
	s_add_i32 s27, 0, 0x18000
	v_add_u32_e32 v143, s27, v141
	s_add_i32 s28, 0, 0x1c000
	ds_read_b128 v[144:147], v143
	ds_read_b128 v[148:151], v143 offset:1024
	ds_read_b128 v[152:155], v143 offset:2048
	ds_read_b128 v[156:159], v143 offset:3072
	v_add_u32_e32 v143, s28, v141
	ds_read_b128 v[160:163], v143
	ds_read_b128 v[164:167], v143 offset:1024
	ds_read_b128 v[168:171], v143 offset:2048
	ds_read_b128 v[174:177], v143 offset:3072
	s_add_u32 s12, s12, 0x80000
	s_addc_u32 s13, s13, 0
	s_mov_b32 m0, s14
	v_lshl_add_u64 v[220:221], s[12:13], 0, v[132:133]
	ds_read_b128 v[178:181], v142 offset:32768
	ds_read_b128 v[182:185], v142 offset:33792
	ds_read_b128 v[186:189], v142 offset:34816
	ds_read_b128 v[190:193], v142 offset:35840
	ds_read_b128 v[194:197], v142 offset:36864
	ds_read_b128 v[198:201], v142 offset:37888
	ds_read_b128 v[202:205], v142 offset:38912
	ds_read_b128 v[210:213], v142 offset:39936
	global_load_lds_dwordx4 v[220:221], off
	v_lshl_add_u64 v[220:221], s[12:13], 0, v[134:135]
	s_mov_b32 m0, s15
	s_nop 0
	global_load_lds_dwordx4 v[220:221], off
	s_waitcnt vmcnt(8)
	s_waitcnt lgkmcnt(0)
	s_barrier
	s_setprio 1
	s_waitcnt lgkmcnt(0)
	v_mfma_f32_16x16x32_bf16 v[126:129], v[144:147], v[178:181], v[126:129]
	v_mfma_f32_16x16x32_bf16 v[126:129], v[148:151], v[182:185], v[126:129]
	v_mfma_f32_16x16x32_bf16 v[122:125], v[156:159], v[182:185], v[122:125]
	v_mfma_f32_16x16x32_bf16 v[122:125], v[152:155], v[178:181], v[122:125]
	v_mfma_f32_16x16x32_bf16 v[106:109], v[152:155], v[186:189], v[106:109]
	v_mfma_f32_16x16x32_bf16 v[106:109], v[156:159], v[190:193], v[106:109]
	v_mfma_f32_16x16x32_bf16 v[110:113], v[148:151], v[190:193], v[110:113]
	v_mfma_f32_16x16x32_bf16 v[110:113], v[144:147], v[186:189], v[110:113]
	v_mfma_f32_16x16x32_bf16 v[94:97], v[144:147], v[194:197], v[94:97]
	v_mfma_f32_16x16x32_bf16 v[94:97], v[148:151], v[198:201], v[94:97]
	v_mfma_f32_16x16x32_bf16 v[90:93], v[156:159], v[198:201], v[90:93]
	v_mfma_f32_16x16x32_bf16 v[90:93], v[152:155], v[194:197], v[90:93]
	v_mfma_f32_16x16x32_bf16 v[74:77], v[152:155], v[202:205], v[74:77]
	v_mfma_f32_16x16x32_bf16 v[74:77], v[156:159], v[210:213], v[74:77]
	v_mfma_f32_16x16x32_bf16 v[78:81], v[148:151], v[210:213], v[78:81]
	v_mfma_f32_16x16x32_bf16 v[78:81], v[144:147], v[202:205], v[78:81]
	s_setprio 0
	s_setprio 1
	v_mfma_f32_16x16x32_bf16 v[118:121], v[160:163], v[178:181], v[118:121]
	v_mfma_f32_16x16x32_bf16 v[118:121], v[164:167], v[182:185], v[118:121]
	v_mfma_f32_16x16x32_bf16 v[114:117], v[174:177], v[182:185], v[114:117]
	v_mfma_f32_16x16x32_bf16 v[114:117], v[168:171], v[178:181], v[114:117]
	v_mfma_f32_16x16x32_bf16 v[98:101], v[168:171], v[186:189], v[98:101]
	v_mfma_f32_16x16x32_bf16 v[98:101], v[174:177], v[190:193], v[98:101]
	v_mfma_f32_16x16x32_bf16 v[102:105], v[164:167], v[190:193], v[102:105]
	v_mfma_f32_16x16x32_bf16 v[102:105], v[160:163], v[186:189], v[102:105]
	v_mfma_f32_16x16x32_bf16 v[86:89], v[160:163], v[194:197], v[86:89]
	v_mfma_f32_16x16x32_bf16 v[86:89], v[164:167], v[198:201], v[86:89]
	v_mfma_f32_16x16x32_bf16 v[82:85], v[174:177], v[198:201], v[82:85]
	v_mfma_f32_16x16x32_bf16 v[82:85], v[168:171], v[194:197], v[82:85]
	v_mfma_f32_16x16x32_bf16 v[66:69], v[168:171], v[202:205], v[66:69]
	v_mfma_f32_16x16x32_bf16 v[66:69], v[174:177], v[210:213], v[66:69]
	v_mfma_f32_16x16x32_bf16 v[70:73], v[164:167], v[210:213], v[70:73]
	v_mfma_f32_16x16x32_bf16 v[70:73], v[160:163], v[202:205], v[70:73]
	s_setprio 0
	s_barrier
	s_add_i32 s12, s27, s18
	v_lshl_add_u64 v[206:207], v[206:207], 0, s[68:69]
	s_mov_b32 m0, s12
	ds_read_b128 v[178:181], v142 offset:49152
	ds_read_b128 v[182:185], v142 offset:50176
	ds_read_b128 v[186:189], v142 offset:51200
	ds_read_b128 v[190:193], v142 offset:52224
	ds_read_b128 v[194:197], v142 offset:53248
	ds_read_b128 v[198:201], v142 offset:54272
	ds_read_b128 v[202:205], v142 offset:55296
	ds_read_b128 v[210:213], v142 offset:56320
	global_load_lds_dwordx4 v[206:207], off
	s_add_i32 m0, s12, 0x2000
	s_add_u32 s10, s10, 0x80080
	v_lshl_add_u64 v[206:207], v[214:215], 0, s[68:69]
	s_addc_u32 s11, s11, 0
	s_add_i32 s12, s28, s18
	global_load_lds_dwordx4 v[206:207], off
	v_lshl_add_u64 v[206:207], s[10:11], 0, v[0:1]
	s_mov_b32 m0, s12
	s_nop 0
	global_load_lds_dwordx4 v[206:207], off
	v_lshl_add_u64 v[206:207], s[10:11], 0, v[130:131]
	s_add_i32 m0, s12, 0x2000
	s_nop 0
	global_load_lds_dwordx4 v[206:207], off
	v_lshl_add_u64 v[206:207], v[216:217], 0, s[68:69]
	s_mov_b32 m0, s20
	s_nop 0
	global_load_lds_dwordx4 v[206:207], off
	v_lshl_add_u64 v[206:207], v[218:219], 0, s[68:69]
	s_mov_b32 m0, s21
	s_nop 0
	global_load_lds_dwordx4 v[206:207], off
	s_waitcnt vmcnt(8)
	s_waitcnt lgkmcnt(0)
	s_barrier
	s_setprio 1
	s_waitcnt lgkmcnt(0)
	v_mfma_f32_16x16x32_bf16 v[62:65], v[144:147], v[178:181], v[62:65]
	v_mfma_f32_16x16x32_bf16 v[62:65], v[148:151], v[182:185], v[62:65]
	v_mfma_f32_16x16x32_bf16 v[58:61], v[156:159], v[182:185], v[58:61]
	v_mfma_f32_16x16x32_bf16 v[58:61], v[152:155], v[178:181], v[58:61]
	v_mfma_f32_16x16x32_bf16 v[42:45], v[152:155], v[186:189], v[42:45]
	v_mfma_f32_16x16x32_bf16 v[42:45], v[156:159], v[190:193], v[42:45]
	v_mfma_f32_16x16x32_bf16 v[46:49], v[148:151], v[190:193], v[46:49]
	v_mfma_f32_16x16x32_bf16 v[46:49], v[144:147], v[186:189], v[46:49]
	v_mfma_f32_16x16x32_bf16 v[30:33], v[144:147], v[194:197], v[30:33]
	v_mfma_f32_16x16x32_bf16 v[30:33], v[148:151], v[198:201], v[30:33]
	v_mfma_f32_16x16x32_bf16 v[26:29], v[156:159], v[198:201], v[26:29]
	v_mfma_f32_16x16x32_bf16 v[26:29], v[152:155], v[194:197], v[26:29]
	v_mfma_f32_16x16x32_bf16 v[10:13], v[152:155], v[202:205], v[10:13]
	v_mfma_f32_16x16x32_bf16 v[10:13], v[156:159], v[210:213], v[10:13]
	v_mfma_f32_16x16x32_bf16 v[14:17], v[148:151], v[210:213], v[14:17]
	v_mfma_f32_16x16x32_bf16 v[14:17], v[144:147], v[202:205], v[14:17]
	s_setprio 0
	s_setprio 1
	v_mfma_f32_16x16x32_bf16 v[54:57], v[160:163], v[178:181], v[54:57]
	v_mfma_f32_16x16x32_bf16 v[54:57], v[164:167], v[182:185], v[54:57]
	v_mfma_f32_16x16x32_bf16 v[50:53], v[174:177], v[182:185], v[50:53]
	v_mfma_f32_16x16x32_bf16 v[50:53], v[168:171], v[178:181], v[50:53]
	v_mfma_f32_16x16x32_bf16 v[34:37], v[168:171], v[186:189], v[34:37]
	v_mfma_f32_16x16x32_bf16 v[34:37], v[174:177], v[190:193], v[34:37]
	v_mfma_f32_16x16x32_bf16 v[38:41], v[164:167], v[190:193], v[38:41]
	v_mfma_f32_16x16x32_bf16 v[38:41], v[160:163], v[186:189], v[38:41]
	v_mfma_f32_16x16x32_bf16 v[22:25], v[160:163], v[194:197], v[22:25]
	v_mfma_f32_16x16x32_bf16 v[22:25], v[164:167], v[198:201], v[22:25]
	v_mfma_f32_16x16x32_bf16 v[18:21], v[174:177], v[198:201], v[18:21]
	v_mfma_f32_16x16x32_bf16 v[18:21], v[168:171], v[194:197], v[18:21]
	v_mfma_f32_16x16x32_bf16 v[2:5], v[168:171], v[202:205], v[2:5]
	v_mfma_f32_16x16x32_bf16 v[2:5], v[174:177], v[210:213], v[2:5]
	v_mfma_f32_16x16x32_bf16 v[6:9], v[164:167], v[210:213], v[6:9]
	v_mfma_f32_16x16x32_bf16 v[6:9], v[160:163], v[202:205], v[6:9]
	s_setprio 0
	s_barrier
	s_add_i32 s26, s26, 2
	s_add_u32 s8, s8, 0x100
	s_addc_u32 s9, s9, 0
	s_cmp_gt_u32 s26, 29
	s_cbranch_scc0 .LBB0_376
	s_cmpk_lt_u32 s17, 0x100
	s_cbranch_scc0 .LBB0_379
	s_barrier
